# v62 + attention step 0: K0 fragment and c-value LDS reads issued up front with counted waits
# speedup vs baseline: 1.0066x; 1.0066x over previous
.Lmy_w2_skip:
	s_or_b64 exec, exec, s[0:1]
	ds_read_b128 v[2:5], v216
	ds_read_b128 v[74:77], v216 offset:512
	ds_read_b128 v[78:81], v216 offset:2048
	ds_read_b128 v[82:85], v216 offset:2560
	ds_read_b128 v[86:89], v216 offset:4096
	ds_read_b128 v[90:93], v216 offset:4608
	ds_read_b128 v[94:97], v216 offset:6144
	ds_read_b128 v[98:101], v216 offset:6656
	v_lshlrev_b32_e32 v217, 4, v208
	v_add_u32_e32 v0, 0, v217
	v_add_u32_e32 v0, 0x14800, v0
	s_lshr_b32 s11, s11, 6
	s_sub_i32 s86, s11, s10
	ds_read_b128 v[20:23], v0
	ds_read_b128 v[24:27], v0 offset:128
	ds_read_b128 v[28:31], v0 offset:32
	ds_read_b128 v[50:53], v0 offset:160
	ds_read_b128 v[54:57], v0 offset:64
	ds_read_b128 v[58:61], v0 offset:192
	ds_read_b128 v[62:65], v0 offset:96
	ds_read_b128 v[66:69], v0 offset:224
	s_waitcnt lgkmcnt(14)
	v_mfma_f32_32x32x16_bf16 v[32:47], v[74:77], v[124:127], 0
	v_or_b32_e32 v215, s82, v207
	v_mfma_f32_32x32x16_bf16 v[4:19], v[2:5], v[124:127], 0
	s_waitcnt lgkmcnt(13)
	v_mfma_f32_32x32x16_bf16 v[4:19], v[78:81], v[120:123], v[4:19]
	s_waitcnt lgkmcnt(12)
	v_mfma_f32_32x32x16_bf16 v[32:47], v[82:85], v[120:123], v[32:47]
	s_waitcnt lgkmcnt(11)
	v_mfma_f32_32x32x16_bf16 v[4:19], v[86:89], v[116:119], v[4:19]
	s_waitcnt lgkmcnt(10)
	v_mfma_f32_32x32x16_bf16 v[32:47], v[90:93], v[116:119], v[32:47]
	s_waitcnt lgkmcnt(9)
	v_mfma_f32_32x32x16_bf16 v[4:19], v[94:97], v[112:115], v[4:19]
	s_waitcnt lgkmcnt(8)
	v_mfma_f32_32x32x16_bf16 v[32:47], v[98:101], v[112:115], v[32:47]
	s_nop 15
	s_nop 7
	s_waitcnt lgkmcnt(7)
	v_sub_f32_e32 v3, v7, v23
	v_sub_f32_e32 v2, v6, v22
	v_sub_f32_e32 v23, v5, v21
	v_sub_f32_e32 v0, v4, v20
	s_waitcnt lgkmcnt(5)
	v_sub_f32_e32 v7, v11, v31
	v_sub_f32_e32 v6, v10, v30
	v_sub_f32_e32 v5, v9, v29
	v_sub_f32_e32 v4, v8, v28
	s_waitcnt lgkmcnt(3)
	v_sub_f32_e32 v11, v15, v57
	v_sub_f32_e32 v10, v14, v56
	v_sub_f32_e32 v9, v13, v55
	v_sub_f32_e32 v8, v12, v54
	s_waitcnt lgkmcnt(1)
	v_sub_f32_e32 v15, v19, v65
	v_sub_f32_e32 v14, v18, v64
	v_sub_f32_e32 v13, v17, v63
	v_sub_f32_e32 v12, v16, v62
	v_sub_f32_e32 v31, v35, v27
	v_sub_f32_e32 v28, v34, v26
	v_sub_f32_e32 v33, v33, v25
	v_sub_f32_e32 v30, v32, v24
	v_sub_f32_e32 v27, v39, v53
	v_sub_f32_e32 v24, v38, v52
	v_sub_f32_e32 v29, v37, v51
	v_sub_f32_e32 v26, v36, v50
	v_sub_f32_e32 v21, v43, v61
	v_sub_f32_e32 v20, v42, v60
	v_sub_f32_e32 v25, v41, v59
	v_sub_f32_e32 v22, v40, v58
	s_waitcnt lgkmcnt(0)
	v_sub_f32_e32 v17, v47, v69
	v_sub_f32_e32 v16, v46, v68
	v_sub_f32_e32 v19, v45, v67
	v_sub_f32_e32 v18, v44, v66
	s_cmp_gt_i32 s86, 4
	v_lshlrev_b32_e32 v211, 2, v208
	s_cbranch_scc1 .LBB0_562
	s_lshl_b32 s0, s86, 6
	v_subrev_u32_e32 v32, s0, v211
	v_add_u32_e32 v35, 0x120, v32
	v_add_u32_e32 v34, 0x100, v32
	v_cmp_le_i32_e64 s[0:1], v35, v215
	v_cmp_le_i32_e32 vcc, v34, v215
	s_nop 0
	v_cndmask_b32_e64 v30, v204, v30, s[0:1]
	v_cmp_lt_i32_e64 s[0:1], v34, v215
	v_add_u32_e32 v34, 0x121, v32
	v_cndmask_b32_e32 v0, v204, v0, vcc
	v_cmp_le_i32_e32 vcc, v34, v215
	v_add_u32_e32 v34, 0x102, v32
	v_cndmask_b32_e64 v23, v204, v23, s[0:1]
	v_cndmask_b32_e32 v33, v204, v33, vcc
	v_cmp_le_i32_e32 vcc, v34, v215
	v_add_u32_e32 v34, 0x122, v32
	s_nop 0
	v_cndmask_b32_e32 v2, v204, v2, vcc
	v_cmp_le_i32_e32 vcc, v34, v215
	v_add_u32_e32 v34, 0x103, v32
	s_nop 0
	v_cndmask_b32_e32 v28, v204, v28, vcc
	v_cmp_le_i32_e32 vcc, v34, v215
	v_add_u32_e32 v34, 0x123, v32
	s_nop 0
	v_cndmask_b32_e32 v3, v204, v3, vcc
	v_cmp_le_i32_e32 vcc, v34, v215
	v_add_u32_e32 v34, 0x108, v32
	s_nop 0
	v_cndmask_b32_e32 v31, v204, v31, vcc
	v_cmp_le_i32_e32 vcc, v34, v215
	v_add_u32_e32 v34, 0x128, v32
	s_nop 0
	v_cndmask_b32_e32 v4, v204, v4, vcc
	v_cmp_le_i32_e32 vcc, v34, v215
	v_add_u32_e32 v34, 0x109, v32
	s_nop 0
	v_cndmask_b32_e32 v26, v204, v26, vcc
	v_cmp_le_i32_e32 vcc, v34, v215
	v_add_u32_e32 v34, 0x129, v32
	s_nop 0
	v_cndmask_b32_e32 v5, v204, v5, vcc
	v_cmp_le_i32_e32 vcc, v34, v215
	v_add_u32_e32 v34, 0x10a, v32
	s_nop 0
	v_cndmask_b32_e32 v29, v204, v29, vcc
	v_cmp_le_i32_e32 vcc, v34, v215
	v_add_u32_e32 v34, 0x12a, v32
	s_nop 0
	v_cndmask_b32_e32 v6, v204, v6, vcc
	v_cmp_le_i32_e32 vcc, v34, v215
	v_add_u32_e32 v34, 0x10b, v32
	s_nop 0
	v_cndmask_b32_e32 v24, v204, v24, vcc
	v_cmp_le_i32_e32 vcc, v34, v215
	v_add_u32_e32 v34, 0x12b, v32
	s_nop 0
	v_cndmask_b32_e32 v7, v204, v7, vcc
	v_cmp_le_i32_e32 vcc, v34, v215
	v_add_u32_e32 v34, 0x110, v32
	s_nop 0
	v_cndmask_b32_e32 v27, v204, v27, vcc
	v_cmp_le_i32_e32 vcc, v34, v215
	v_add_u32_e32 v34, 0x130, v32
	s_nop 0
	v_cndmask_b32_e32 v8, v204, v8, vcc
	v_cmp_le_i32_e32 vcc, v34, v215
	v_add_u32_e32 v34, 0x111, v32
	s_nop 0
	v_cndmask_b32_e32 v22, v204, v22, vcc
	v_cmp_le_i32_e32 vcc, v34, v215
	v_add_u32_e32 v34, 0x131, v32
	s_nop 0
	v_cndmask_b32_e32 v9, v204, v9, vcc
	v_cmp_le_i32_e32 vcc, v34, v215
	v_add_u32_e32 v34, 0x112, v32
	s_nop 0
	v_cndmask_b32_e32 v25, v204, v25, vcc
	v_cmp_le_i32_e32 vcc, v34, v215
	v_add_u32_e32 v34, 0x132, v32
	s_nop 0
	v_cndmask_b32_e32 v10, v204, v10, vcc
	v_cmp_le_i32_e32 vcc, v34, v215
	v_add_u32_e32 v34, 0x113, v32
	s_nop 0
	v_cndmask_b32_e32 v20, v204, v20, vcc
	v_cmp_le_i32_e32 vcc, v34, v215
	v_add_u32_e32 v34, 0x133, v32
	s_nop 0
	v_cndmask_b32_e32 v11, v204, v11, vcc
	v_cmp_le_i32_e32 vcc, v34, v215
	v_add_u32_e32 v34, 0x118, v32
	s_nop 0
	v_cndmask_b32_e32 v21, v204, v21, vcc
	v_cmp_le_i32_e32 vcc, v34, v215
	v_add_u32_e32 v34, 0x138, v32
	s_nop 0
	v_cndmask_b32_e32 v12, v204, v12, vcc
	v_cmp_le_i32_e32 vcc, v34, v215
	v_add_u32_e32 v34, 0x119, v32
	s_nop 0
	v_cndmask_b32_e32 v18, v204, v18, vcc
	v_cmp_le_i32_e32 vcc, v34, v215
	v_add_u32_e32 v34, 0x139, v32
	s_nop 0
	v_cndmask_b32_e32 v13, v204, v13, vcc
	v_cmp_le_i32_e32 vcc, v34, v215
	v_add_u32_e32 v34, 0x11a, v32
	s_nop 0
	v_cndmask_b32_e32 v19, v204, v19, vcc
	v_cmp_le_i32_e32 vcc, v34, v215
	v_add_u32_e32 v34, 0x13a, v32
	s_nop 0
	v_cndmask_b32_e32 v14, v204, v14, vcc
	v_cmp_le_i32_e32 vcc, v34, v215
	v_add_u32_e32 v34, 0x11b, v32
	v_add_u32_e32 v32, 0x13b, v32
	v_cndmask_b32_e32 v16, v204, v16, vcc
	v_cmp_le_i32_e32 vcc, v34, v215
	s_nop 1
	v_cndmask_b32_e32 v15, v204, v15, vcc
	v_cmp_le_i32_e32 vcc, v32, v215
	s_nop 1
	v_cndmask_b32_e32 v17, v204, v17, vcc
